# indexer loop: tile byte offset by one 32-bit shift, redundant vmcnt wait dropped, out-of-range ticket path moved out of line
# speedup vs baseline: 1.0001x; 1.0001x over previous
.LBB0_696:
	s_or_b64 exec, exec, s[6:7]
	s_add_i32 s6, s52, 3
	s_ashr_i32 s13, s6, 5
	s_ashr_i32 s51, s50, 31
	s_and_b32 s14, s13, 0xffffffe0
	s_add_i32 s10, s14, 32
	s_ashr_i32 s53, s60, 6
	s_lshl_b64 s[6:7], s[50:51], 20
	v_and_b32_e32 v145, 63, v144
	v_bfe_u32 v162, v144, 5, 1
	s_add_u32 s6, s40, s6
	v_lshlrev_b32_e32 v163, 1, v162
	s_addc_u32 s7, s41, s7
	v_lshlrev_b32_e32 v132, 4, v145
	v_and_b32_e32 v164, 31, v144
	v_lshlrev_b32_e32 v167, 16, v162
	v_lshl_add_u32 v165, v162, 13, s68
	v_add_u32_e32 v1, s52, v163
	v_lshl_add_u64 v[156:157], s[6:7], 0, v[132:133]
	v_lshl_add_u32 v166, v145, 2, s71
	s_waitcnt lgkmcnt(0)
	s_barrier
	s_waitcnt vmcnt(8)
	v_swap_b32 v135, v36
	v_swap_b32 v137, v38
	v_swap_b32 v139, v40
	v_swap_b32 v141, v42
	v_add_u32_e32 v132, 1, v1
	v_lshlrev_b32_e32 v168, 2, v164
	v_mov_b32_e32 v172, 0x25a00
	s_mov_b32 s16, s53
	s_add_i32 s17, s53, 8
	s_mov_b32 s10, 0
	s_mov_b32 s18, 0x80000000
	s_mov_b32 s7, 0
	s_mov_b32 s11, 0xffff
	s_add_i32 s19, s52, -31
	s_ashr_i32 s19, s19, 5
	v_add_u32_e32 v100, s73, v165
	v_add_u32_e32 v175, v167, v168
	s_mov_b64 exec, 1
	ds_add_rtn_u32 v171, v172, v149
	s_mov_b64 exec, -1
	s_waitcnt lgkmcnt(0)
	v_readfirstlane_b32 s15, v171
	s_mov_b32 s14, -1
	s_branch .Lidx_entry0
.Lidx_loop:
	s_mov_b32 s14, s17
	s_mov_b32 s17, s15
	s_mov_b64 exec, 1
	ds_add_rtn_u32 v171, v172, v149
	s_mov_b64 exec, -1
	s_cmp_gt_i32 s17, s13
	s_cbranch_scc1 .Lidx_dummy0
	s_lshl_b32 s6, s17, 12
	v_lshl_add_u64 v[84:85], v[156:157], 0, s[6:7]
	global_load_dwordx4 v[96:99], v[84:85], off
	global_load_dwordx4 v[92:95], v[84:85], off offset:1024
	global_load_dwordx4 v[88:91], v[84:85], off offset:2048
	s_nop 0
	global_load_dwordx4 v[84:87], v[84:85], off offset:3072

.Lidx_join0:
	v_readfirstlane_b32 s15, v171
	s_mov_b32 s14, s16
	s_mov_b32 s16, s15
	s_mov_b64 exec, 1
	ds_add_rtn_u32 v171, v172, v149
	s_mov_b64 exec, -1
	s_cmp_gt_i32 s16, s13
	s_cbranch_scc1 .Lidx_dummy1
	s_lshl_b32 s6, s16, 12
	v_lshl_add_u64 v[68:69], v[156:157], 0, s[6:7]
	global_load_dwordx4 v[80:83], v[68:69], off
	global_load_dwordx4 v[76:79], v[68:69], off offset:1024
	global_load_dwordx4 v[72:75], v[68:69], off offset:2048
	s_nop 0
	global_load_dwordx4 v[68:71], v[68:69], off offset:3072

.Lidx_dummy0:
	global_load_dword v173, v133, s[40:41]
	global_load_dword v173, v133, s[40:41]
	global_load_dword v173, v133, s[40:41]
	global_load_dword v173, v133, s[40:41]
	s_branch .Lidx_lddone0

.LBB0_975:
	s_or_b64 exec, exec, s[4:5]
	v_mov_b32_e32 v15, v202
	s_add_u32 s62, s28, 0x14000000
	s_waitcnt lgkmcnt(0)
	s_barrier
	s_nop 0
	s_nop 0
	s_nop 0
	s_nop 0
	s_nop 0
	s_nop 0
	s_nop 0
	s_nop 0
	s_nop 0
	s_nop 0
	s_nop 0
	s_nop 0
	s_nop 0
	s_nop 0
	s_nop 0
	s_nop 0
	s_nop 0
	s_addc_u32 s63, s29, 0
	v_readfirstlane_b32 s4, v15
	s_ashr_i32 s4, s4, 6
	s_and_b64 s[6:7], s[46:47], exec
	s_cselect_b32 s5, 8, 1
	v_cvt_f32_ubyte0_e32 v1, s5
	v_rcp_iflag_f32_e32 v1, v1
	s_add_i32 s8, s5, -1
	s_and_b64 s[6:7], s[46:47], exec
	s_cselect_b32 s24, 3, 0
	v_mul_f32_e32 v1, 0x4f7ffffe, v1
	v_cvt_u32_f32_e32 v1, v1
	s_sub_i32 s9, 0, s5
	s_abs_i32 s7, s30
	s_lshr_b32 s6, s2, s24
	v_readfirstlane_b32 s10, v1
	s_mul_i32 s9, s9, s10
	s_mul_hi_u32 s9, s10, s9
	s_add_i32 s10, s10, s9
	s_mul_hi_u32 s9, s7, s10
	s_mul_i32 s10, s9, s5
	s_sub_i32 s7, s7, s10
	s_lshl_b32 s6, s6, 3
	s_ashr_i32 s68, s30, 31
	s_add_i32 s10, s9, 1
	s_sub_i32 s11, s7, s5
	s_cmp_ge_u32 s7, s5
	s_cselect_b32 s9, s10, s9
	s_cselect_b32 s7, s11, s7
	s_add_i32 s10, s9, 1
	s_cmp_ge_u32 s7, s5
	s_cselect_b32 s7, s10, s9
	s_xor_b32 s7, s7, s68
	s_sub_i32 s7, s7, s68
	s_lshl_b32 s25, s7, 3
	s_abs_i32 s7, s25
	v_cvt_f32_u32_e32 v1, s7
	s_add_i32 s40, s4, s6
	s_sub_i32 s6, s25, s40
	s_and_b32 s41, s8, s2
	v_rcp_iflag_f32_e32 v1, v1
	s_add_i32 s8, s6, 0x1fff
	s_sub_i32 s6, 0xffffe001, s6
	s_xor_b32 s9, s8, s25
	v_mul_f32_e32 v1, 0x4f7ffffe, v1
	v_cvt_u32_f32_e32 v1, v1
	s_max_i32 s6, s8, s6
	s_sub_i32 s8, 0, s7
	s_ashr_i32 s9, s9, 31
	v_readfirstlane_b32 s10, v1
	s_mul_i32 s8, s8, s10
	s_mul_hi_u32 s8, s10, s8
	s_add_i32 s10, s10, s8
	s_mul_hi_u32 s8, s6, s10
	s_mul_i32 s10, s8, s7
	s_sub_i32 s6, s6, s10
	s_add_i32 s10, s8, 1
	s_sub_i32 s11, s6, s7
	s_cmp_ge_u32 s6, s7
	s_cselect_b32 s8, s10, s8
	s_cselect_b32 s6, s11, s6
	s_add_i32 s10, s8, 1
	s_cmp_ge_u32 s6, s7
	s_cselect_b32 s6, s10, s8
	s_sub_i32 s5, s5, s41
	s_xor_b32 s6, s6, s9
	s_add_i32 s5, s5, 15
	s_sub_i32 s42, s6, s9
	s_lshr_b32 s5, s5, s24
	s_mul_i32 s43, s42, s5
	s_cmp_lt_i32 s43, 1
	s_mov_b32 s9, 0
	s_cbranch_scc1 .LBB0_980
	s_lshl_b32 s5, s4, 14
	s_lshl_b32 s4, s4, 10
	s_add_i32 s47, s4, 0
	s_lshr_b32 s8, s41, 2
	s_add_i32 s46, s5, 0
	s_add_i32 s47, s47, 0x20000
	s_and_b32 s10, s41, 3
	s_lshl_b64 s[4:5], s[8:9], 13
	s_ashr_i32 s6, s40, 31
	s_add_u32 s4, s4, s40
	s_addc_u32 s5, s5, s6
	s_lshl_b64 s[6:7], s[4:5], 9
	v_and_b32_e32 v14, 63, v15
	s_add_u32 s6, s44, s6
	s_addc_u32 s7, s45, s7
	v_lshlrev_b32_e32 v42, 3, v14
	global_load_dwordx2 v[2:3], v42, s[6:7]
	v_and_b32_e32 v17, 15, v15
	v_bfe_u32 v4, v15, 4, 2
	v_bfe_u32 v6, v15, 2, 2
	v_and_b32_e32 v1, 7, v15
	v_lshlrev_b32_e32 v34, 3, v15
	v_mov_b32_e32 v7, 0x1000
	v_lshrrev_b32_e32 v9, 3, v15
	v_or_b32_e32 v12, 16, v17
	v_lshl_or_b32 v6, v4, 2, v6
	v_bfe_u32 v5, v15, 3, 1
	v_and_b32_e32 v10, 1, v15
	v_bitop3_b32 v13, v4, v1, 4 bitop3:0x36
	v_bitop3_b32 v16, v4, v15, 7 bitop3:0x78
	v_and_or_b32 v7, v34, 24, v7
	v_xor_b32_e32 v9, v9, v15
	v_mul_u32_u24_e32 v21, 0x40004, v14
	v_lshrrev_b32_e32 v22, 3, v12
	v_lshlrev_b32_e32 v24, 4, v6
	v_lshlrev_b32_e32 v6, 7, v6
	s_cmpk_gt_i32 s40, 0xff
	s_movk_i32 s6, 0x60
	v_lshlrev_b32_e32 v12, 7, v12
	v_xor_b32_e32 v23, v13, v5
	v_xor_b32_e32 v5, v16, v5
	v_and_or_b32 v9, v9, 6, v10
	v_or_b32_e32 v60, 0x10000, v21
	v_or_b32_e32 v61, 0x30002, v21
	v_xor_b32_e32 v10, v13, v22
	v_xor_b32_e32 v13, v16, v22
	v_or_b32_e32 v16, 0x800, v6
	v_or_b32_e32 v6, v6, v7
	s_cselect_b64 vcc, -1, 0
	v_lshlrev_b32_e32 v11, 6, v15
	s_waitcnt vmcnt(2)
	v_lshlrev_b32_e32 v52, 4, v9
	v_add_u32_e32 v9, s47, v42
	v_lshl_or_b32 v37, v10, 4, v12
	v_bitop3_b32 v10, v24, v16, s6 bitop3:0xce
	v_bitop3_b32 v39, v24, v6, s6 bitop3:0xce
	s_mul_hi_u32 s6, s4, 0x1200
	s_mulk_i32 s5, 0x1200
	s_mulk_i32 s4, 0x1200
	s_add_i32 s6, s6, s5
	v_mov_b32_e32 v43, 0
	s_add_u32 s4, s38, s4
	v_mov_b32_e32 v8, 0x60
	v_lshlrev_b32_e32 v19, 7, v17
	s_addc_u32 s5, s39, s6
	v_lshl_or_b32 v35, v23, 4, v19
	v_lshl_or_b32 v36, v5, 4, v19
	v_and_b32_e32 v5, 0x60, v24
	v_bitop3_b32 v19, v24, 64, v8 bitop3:0x6c
	v_bitop3_b32 v8, v24, 32, v8 bitop3:0x6c
	v_bfe_u32 v18, v15, 3, 3
	v_lshl_or_b32 v38, v13, 4, v12
	v_or_b32_e32 v12, v19, v16
	v_or_b32_e32 v13, v8, v16
	v_or_b32_e32 v41, v8, v6
	v_or_b32_e32 v8, v5, v16
	s_waitcnt vmcnt(1)
	v_or_b32_e32 v56, v6, v5
	v_lshlrev_b32_e32 v16, 3, v4
	v_and_b32_e32 v4, 48, v15
	v_mov_b32_e32 v5, v43
	v_lshlrev_b32_e32 v63, 6, v18
	v_bitop3_b32 v20, v18, v15, 7 bitop3:0x78
	v_or_b32_e32 v40, v19, v6
	v_add_u32_e32 v57, v10, v7
	v_add_u32_e32 v58, v12, v7
	v_add_u32_e32 v59, v13, v7
	v_add_u32_e32 v90, v8, v7
	v_add_u32_e32 v18, s47, v63
	v_mov_b32_e32 v19, v43
	v_lshlrev_b32_e32 v44, 4, v20
	v_mov_b32_e32 v45, v43
	s_mov_b32 m0, s46
	v_mov_b32_e32 v53, v43
	v_mov_b32_e32 v64, 9
	v_xor_b32_e32 v50, 16, v44
	v_mov_b32_e32 v51, v43
	v_xor_b32_e32 v48, 32, v44
	s_waitcnt vmcnt(0)
	v_cndmask_b32_e32 v2, v60, v2, vcc
	v_cndmask_b32_e32 v3, v61, v3, vcc
	ds_write_b64 v9, v[2:3]
	v_and_b32_e32 v2, 0xc0, v11
	v_lshlrev_b32_e32 v62, 1, v2
	v_lshl_or_b32 v2, s10, 9, v62
	v_mov_b32_e32 v3, v43
	v_lshl_add_u64 v[2:3], s[4:5], 0, v[2:3]
	s_lshl_b64 s[4:5], s[8:9], 22
	s_add_u32 s6, s80, s4
	v_lshl_add_u64 v[2:3], v[2:3], 0, v[4:5]
	s_addc_u32 s7, s81, s5
	global_load_dwordx4 v[10:13], v[2:3], off
	global_load_dwordx4 v[6:9], v[2:3], off offset:64
	s_waitcnt lgkmcnt(0)
	s_add_u32 s4, s37, s4
	ds_read_b128 v[30:33], v18
	ds_read_b128 v[22:25], v18 offset:16
	ds_read_b128 v[2:5], v18 offset:32
	ds_read_b128 v[26:29], v18 offset:48
	s_addc_u32 s5, s79, s5
	s_lshl_b32 s8, s10, 7
	s_add_u32 s4, s4, s8
	s_addc_u32 s5, s5, 0
	s_waitcnt lgkmcnt(3)
	v_lshlrev_b32_e32 v18, 9, v30
	s_add_u32 s6, s6, s8
	v_and_b32_e32 v18, 0x1fffe00, v18
	s_addc_u32 s7, s7, 0
	v_lshl_add_u64 v[20:21], s[4:5], 0, v[18:19]
	s_add_i32 s48, s46, 0x1000
	v_lshl_add_u64 v[20:21], v[20:21], 0, v[44:45]
	v_lshl_add_u64 v[18:19], s[6:7], 0, v[18:19]
	global_load_lds_dwordx4 v[20:21], off
	v_lshl_add_u64 v[18:19], v[18:19], 0, v[52:53]
	s_mov_b32 m0, s48
	s_add_i32 s49, s46, 0x400
	global_load_lds_dwordx4 v[18:19], off
	v_lshlrev_b32_sdwa v18, v64, v30 dst_sel:DWORD dst_unused:UNUSED_PAD src0_sel:DWORD src1_sel:WORD_1
	v_mov_b32_e32 v19, v43
	v_lshl_add_u64 v[20:21], s[4:5], 0, v[18:19]
	v_lshl_add_u64 v[20:21], v[20:21], 0, v[50:51]
	s_mov_b32 m0, s49
	v_lshl_add_u64 v[18:19], s[6:7], 0, v[18:19]
	s_add_i32 s50, s46, 0x1400
	global_load_lds_dwordx4 v[20:21], off
	v_lshl_add_u64 v[18:19], v[18:19], 0, v[52:53]
	s_mov_b32 m0, s50
	v_mov_b32_e32 v49, v43
	global_load_lds_dwordx4 v[18:19], off
	v_lshlrev_b32_e32 v18, 9, v31
	v_and_b32_e32 v18, 0x1fffe00, v18
	v_mov_b32_e32 v19, v43
	v_lshl_add_u64 v[20:21], s[4:5], 0, v[18:19]
	s_add_i32 s51, s46, 0x800
	v_lshl_add_u64 v[20:21], v[20:21], 0, v[48:49]
	s_mov_b32 m0, s51
	v_lshl_add_u64 v[18:19], s[6:7], 0, v[18:19]
	s_add_i32 s52, s46, 0x1800
	global_load_lds_dwordx4 v[20:21], off
	v_lshl_add_u64 v[18:19], v[18:19], 0, v[52:53]
	s_mov_b32 m0, s52
	v_xor_b32_e32 v46, 48, v44
	global_load_lds_dwordx4 v[18:19], off
	v_lshlrev_b32_sdwa v18, v64, v31 dst_sel:DWORD dst_unused:UNUSED_PAD src0_sel:DWORD src1_sel:WORD_1
	v_mov_b32_e32 v19, v43
	v_lshl_add_u64 v[20:21], s[4:5], 0, v[18:19]
	v_mov_b32_e32 v47, v43
	s_add_i32 s53, s46, 0xc00
	v_lshl_add_u64 v[20:21], v[20:21], 0, v[46:47]
	s_mov_b32 m0, s53
	v_lshl_add_u64 v[18:19], s[6:7], 0, v[18:19]
	s_add_i32 s54, s46, 0x1c00
	global_load_lds_dwordx4 v[20:21], off
	v_lshl_add_u64 v[18:19], v[18:19], 0, v[52:53]
	s_mov_b32 m0, s54
	v_cmp_gt_u32_e64 s[4:5], 4, v17
	global_load_lds_dwordx4 v[18:19], off
	v_and_b32_e32 v17, 0x80, v34
	v_bfe_u32 v15, v15, 5, 1
	v_or_b32_e32 v19, 32, v17
	v_or_b32_e32 v20, 64, v17
	v_or_b32_e32 v21, 0x60, v17
	v_or_b32_e32 v30, 6, v15
	v_or_b32_e32 v82, v17, v30
	v_or_b32_e32 v84, v19, v30
	v_or_b32_e32 v86, v20, v30
	v_or_b32_e32 v88, v21, v30
	v_or_b32_e32 v30, 10, v15
	v_or_b32_e32 v18, 2, v15
	v_or_b32_e32 v98, v17, v30
	v_or_b32_e32 v100, v19, v30
	v_or_b32_e32 v102, v20, v30
	v_or_b32_e32 v104, v21, v30
	v_or_b32_e32 v30, 14, v15
	v_or_b32_e32 v66, v17, v18
	v_or_b32_e32 v68, v19, v18
	v_or_b32_e32 v70, v20, v18
	v_or_b32_e32 v72, v21, v18
	v_or_b32_e32 v18, 4, v15
	v_or_b32_e32 v106, v17, v30
	v_or_b32_e32 v108, v19, v30
	v_or_b32_e32 v110, v20, v30
	v_or_b32_e32 v112, v21, v30
	v_or_b32_e32 v30, 18, v15
	v_or_b32_e32 v81, v17, v18
	v_or_b32_e32 v83, v19, v18
	v_or_b32_e32 v85, v20, v18
	v_or_b32_e32 v87, v21, v18
	v_or_b32_e32 v18, 8, v15
	v_or_b32_e32 v114, v17, v30
	v_or_b32_e32 v116, v19, v30
	v_or_b32_e32 v118, v20, v30
	v_or_b32_e32 v120, v21, v30
	v_or_b32_e32 v30, 22, v15
	v_lshl_add_u64 v[54:55], s[44:45], 0, v[42:43]
	v_or_b32_e32 v97, v17, v18
	v_or_b32_e32 v99, v19, v18
	v_or_b32_e32 v101, v20, v18
	v_or_b32_e32 v103, v21, v18
	v_or_b32_e32 v18, 12, v15
	v_or_b32_e32 v122, v17, v30
	v_or_b32_e32 v124, v19, v30
	v_or_b32_e32 v126, v20, v30
	v_or_b32_e32 v128, v21, v30
	v_or_b32_e32 v30, 26, v15
	s_abs_i32 s45, s42
	v_or_b32_e32 v105, v17, v18
	v_or_b32_e32 v107, v19, v18
	v_or_b32_e32 v109, v20, v18
	v_or_b32_e32 v111, v21, v18
	v_or_b32_e32 v18, 16, v15
	v_or_b32_e32 v130, v17, v30
	v_or_b32_e32 v132, v19, v30
	v_or_b32_e32 v134, v20, v30
	v_or_b32_e32 v136, v21, v30
	v_cvt_f32_u32_e32 v30, s45
	v_or_b32_e32 v113, v17, v18
	v_or_b32_e32 v115, v19, v18
	v_or_b32_e32 v117, v20, v18
	v_or_b32_e32 v119, v21, v18
	v_or_b32_e32 v18, 20, v15
	v_or_b32_e32 v121, v17, v18
	v_or_b32_e32 v123, v19, v18
	v_or_b32_e32 v125, v20, v18
	v_or_b32_e32 v127, v21, v18
	v_or_b32_e32 v18, 24, v15
	v_or_b32_e32 v65, v17, v15
	v_or_b32_e32 v67, v19, v15
	v_or_b32_e32 v69, v20, v15
	v_or_b32_e32 v71, v21, v15
	v_or_b32_e32 v129, v17, v18
	v_or_b32_e32 v131, v19, v18
	v_or_b32_e32 v133, v20, v18
	v_or_b32_e32 v135, v21, v18
	v_or_b32_e32 v18, 28, v15
	v_or_b32_e32 v15, 30, v15
	v_or_b32_e32 v137, v17, v18
	v_or_b32_e32 v138, v17, v15
	v_rcp_iflag_f32_e32 v17, v30
	s_sub_i32 s8, 0, s45
	s_add_i32 s44, s46, 0x2000
	v_lshlrev_b32_e32 v1, 2, v14
	v_mul_f32_e32 v17, 0x4f7ffffe, v17
	v_cvt_u32_f32_e32 v17, v17
	s_waitcnt vmcnt(0)
	v_cndmask_b32_e64 v9, 0, v9, s[4:5]
	v_cndmask_b32_e64 v8, 0, v8, s[4:5]
	v_cndmask_b32_e64 v7, 0, v7, s[4:5]
	v_readfirstlane_b32 s10, v17
	s_mul_i32 s8, s8, s10
	s_mul_hi_u32 s8, s10, s8
	v_cndmask_b32_e64 v6, 0, v6, s[4:5]
	v_cndmask_b32_e64 v13, 0, v13, s[4:5]
	v_cndmask_b32_e64 v12, 0, v12, s[4:5]
	v_cndmask_b32_e64 v11, 0, v11, s[4:5]
	v_cndmask_b32_e64 v10, 0, v10, s[4:5]
	v_cmp_gt_u32_e64 s[6:7], 16, v14
	v_add_u32_e32 v73, s46, v56
	v_add_u32_e32 v74, s46, v90
	v_add_u32_e32 v75, s46, v41
	v_add_u32_e32 v76, s46, v59
	v_add_u32_e32 v77, s46, v40
	v_add_u32_e32 v78, s46, v58
	v_add_u32_e32 v79, s46, v39
	v_add_u32_e32 v80, s46, v57
	v_add_u32_e32 v89, s44, v56
	v_add_u32_e32 v90, s44, v90
	v_add_u32_e32 v91, s44, v41
	v_add_u32_e32 v92, s44, v59
	v_add_u32_e32 v93, s44, v40
	v_add_u32_e32 v94, s44, v58
	v_add_u32_e32 v95, s44, v39
	v_add_u32_e32 v96, s44, v57
	v_or_b32_e32 v139, v19, v18
	v_or_b32_e32 v140, v19, v15
	v_or_b32_e32 v141, v20, v18
	v_or_b32_e32 v142, v20, v15
	v_or_b32_e32 v143, v21, v18
	v_or_b32_e32 v144, v21, v15
	s_ashr_i32 s55, s42, 31
	s_add_i32 s56, s10, s8
	s_sub_i32 s57, 0, s42
	v_lshlrev_b32_e32 v56, 1, v16
	s_add_i32 s58, s46, 0x3000
	s_add_i32 s59, s46, 0x2400
	s_add_i32 s60, s46, 0x3400
	s_add_i32 s61, s46, 0x2800
	s_add_i32 s64, s46, 0x3800
	s_add_i32 s65, s46, 0x2c00
	s_add_i32 s66, s46, 0x3c00
	v_add_u32_e32 v145, s46, v36
	v_add_u32_e32 v149, s46, v35
	v_add_u32_e32 v151, s46, v38
	v_add_u32_e32 v153, s46, v37
	v_lshlrev_b32_e32 v58, 1, v14
	s_movk_i32 s67, 0x7fff
	s_mov_b32 s69, 0
	s_mov_b32 s70, 0
	s_branch .LBB0_978
